# grid barrier: non-leader workgroups poll the top-level generation word directly (no per-XCD relay hop), first boundary uses the XCD barrier instead of cg sync; plus attention V prefetch + max3
# speedup vs baseline: 1.0032x; 1.0032x over previous
; DEV unsigned xb_add(unsigned* p, unsigned v) { return __hip_atomic_fetch_add(p, v, __ATOMIC_RELAXED, __HIP_MEMORY_SCOPE_AGENT); }
; DEV void xcd_barrier(const XcdBarrier& b) {
;     asm volatile("s_waitcnt vmcnt(0)" ::: "memory");
;     __syncthreads();
;     if (threadIdx.x == 0) {
;         unsigned* bar = b.bar;
;         __builtin_amdgcn_s_waitcnt(0);
;         unsigned nloc = b.st[0], nx = b.st[1];
;         if (nloc == 0u) { xcd_barrier_complete(bar, b.x, nloc, nx); b.st[0] = nloc; b.st[1] = nx; }
;         const unsigned old = xb_add(&bar[XB_XSUB(b.x)], 1u);
; __global__ void __launch_bounds__(512, 2) fwd_mega(Params p_unused) {
;     ...
;         if (ph + 1 < ph_hi) { if (ph == ph_lo) cg::this_grid().sync(); else xcd_barrier(xbar); }
.LBB0_1291:
	s_andn2_b64 vcc, exec, s[4:5]
	s_cbranch_vccnz .LBB0_9
	s_add_i32 s36, s57, 1
	s_cmp_ge_i32 s36, s91
	s_cbranch_scc1 .LBB0_9
	s_cmp_lg_u32 s57, s90
	s_mov_b64 s[0:1], -1
	s_waitcnt vmcnt(0)
	s_waitcnt vmcnt(0) lgkmcnt(0)
	s_barrier
	s_mov_b64 s[0:1], exec
	v_readlane_b32 s4, v253, 0
	v_readlane_b32 s5, v253, 1
	s_and_b64 s[4:5], s[0:1], s[4:5]
	s_mov_b64 exec, s[4:5]
	s_cbranch_execz .LBB0_1351
	s_add_i32 s12, 0, 0x20000
	v_mov_b32_e32 v0, s12
	s_waitcnt vmcnt(0) expcnt(0) lgkmcnt(0)
	ds_read_b32 v3, v0
	v_readlane_b32 s4, v254, 38
	s_waitcnt lgkmcnt(0)
	v_cmp_ne_u32_e32 vcc, 0, v3
	v_mov_b32_e32 v0, s4
	ds_read_b32 v2, v0
	s_cbranch_vccnz .LBB0_1314
	s_load_dwordx2 s[4:5], s[92:93], 0x4
	v_readlane_b32 s18, v253, 9
	v_readlane_b32 s20, v253, 11
	v_readlane_b32 s22, v253, 13
	v_readlane_b32 s34, v253, 15
	s_waitcnt lgkmcnt(0)
	s_mul_i32 s13, s4, s71
	v_readlane_b32 s38, v253, 17
	v_readlane_b32 s40, v253, 19
	v_readlane_b32 s42, v253, 21
	v_readlane_b32 s44, v253, 23
	v_readlane_b32 s46, v253, 25
	v_readlane_b32 s48, v253, 27
	v_readlane_b32 s50, v253, 29
	v_readlane_b32 s52, v253, 31
	v_readlane_b32 s54, v253, 33
	v_readlane_b32 s60, v253, 35
	v_readlane_b32 s62, v253, 37
	v_readlane_b32 s66, v253, 39
	v_readlane_b32 s68, v253, 41
	s_mul_i32 s13, s13, s5
	s_mov_b32 s16, 1
	v_readlane_b32 s19, v253, 10
	v_readlane_b32 s21, v253, 12
	v_readlane_b32 s23, v253, 14
	v_readlane_b32 s35, v253, 16
	v_readlane_b32 s39, v253, 18
	v_readlane_b32 s41, v253, 20
	v_readlane_b32 s43, v253, 22
	v_readlane_b32 s45, v253, 24
	v_readlane_b32 s47, v253, 26
	v_readlane_b32 s49, v253, 28
	v_readlane_b32 s51, v253, 30
	v_readlane_b32 s53, v253, 32
	v_readlane_b32 s55, v253, 34
	v_readlane_b32 s61, v253, 36
	v_readlane_b32 s63, v253, 38
	v_readlane_b32 s67, v253, 40
	v_readlane_b32 s69, v253, 42
	s_branch .LBB0_1298

; DEV unsigned xb_ld(unsigned* p)              { return __hip_atomic_load(p, __ATOMIC_RELAXED, __HIP_MEMORY_SCOPE_AGENT); }
; DEV unsigned xb_add(unsigned* p, unsigned v) { return __hip_atomic_fetch_add(p, v, __ATOMIC_RELAXED, __HIP_MEMORY_SCOPE_AGENT); }
; #define XB_SPIN(cond, bar) do { unsigned _sp = 0; while (cond) { __builtin_amdgcn_s_sleep(1); \
;     if ((++_sp & 255u) == 0u) { if (xb_ld(&(bar)[XB_TMO])) break; if (_sp > XB_SPIN_CAP) { atomicAdd(&(bar)[XB_TMO], 1u); break; } } } } while (0)
; DEV void xcd_barrier(const XcdBarrier& b) {
;     ...
;         const unsigned old = xb_add(&bar[XB_XSUB(b.x)], 1u);
;         const unsigned gen = old / nloc;
;         if (old + 1u == (gen + 1u) * nloc) {
;             __builtin_amdgcn_fence(__ATOMIC_RELEASE, "agent");
;             asm volatile("s_waitcnt vmcnt(0)" ::: "memory");
;             const unsigned og = xb_add(&bar[XB_TOP], 1u);
;             const unsigned tg = og / nx;
;             if (og + 1u == (tg + 1u) * nx) xb_add(&bar[XB_TOPGEN], 1u);
;             else XB_SPIN(xb_ld(&bar[XB_TOPGEN]) == tg, bar);
;             __builtin_amdgcn_fence(__ATOMIC_ACQUIRE, "agent");
;             xb_add(&bar[XB_XGEN(b.x)], 1u);
;             asm volatile("s_waitcnt vmcnt(0)" ::: "memory");
;         } else {
;             XB_SPIN(xb_ld(&bar[XB_XGEN(b.x)]) == gen, bar);
.LBB0_1314:
	s_mov_b64 s[6:7], exec
	v_mbcnt_lo_u32_b32 v0, s6, 0
	v_mbcnt_hi_u32_b32 v0, s7, v0
	v_cmp_eq_u32_e32 vcc, 0, v0
	s_and_saveexec_b64 s[4:5], vcc
	v_readlane_b32 s20, v253, 9
	v_readlane_b32 s40, v254, 17
	v_readlane_b32 s21, v253, 10
	v_readlane_b32 s41, v254, 18
	s_cbranch_execz .LBB0_1316
	s_bcnt1_i32_b64 s6, s[6:7]
	v_mov_b32_e32 v4, s6
	v_readlane_b32 s6, v254, 11
	v_readlane_b32 s7, v254, 12
	s_nop 4
	global_atomic_add v4, v1, v4, s[6:7] sc0

; DEV unsigned xb_add(unsigned* p, unsigned v) { return __hip_atomic_fetch_add(p, v, __ATOMIC_RELAXED, __HIP_MEMORY_SCOPE_AGENT); }
; DEV void xcd_barrier(const XcdBarrier& b) {
;     ...
;             __builtin_amdgcn_fence(__ATOMIC_ACQUIRE, "agent");
;             xb_add(&bar[XB_XGEN(b.x)], 1u);
;             asm volatile("s_waitcnt vmcnt(0)" ::: "memory");
.LBB0_1348:
	s_or_b64 exec, exec, s[4:5]
	s_mov_b64 s[4:5], exec
	v_mbcnt_lo_u32_b32 v0, s4, 0
	v_mbcnt_hi_u32_b32 v0, s5, v0
	v_cmp_eq_u32_e32 vcc, 0, v0
	s_waitcnt vmcnt(0)
	buffer_inv sc1
	s_and_saveexec_b64 s[6:7], vcc
	s_cbranch_execz .LBB0_1350
	s_bcnt1_i32_b64 s4, s[4:5]
	v_mov_b32_e32 v0, s4
.LBB0_1350:
	s_or_b64 exec, exec, s[6:7]
	s_waitcnt vmcnt(0)
